# attention loop: next tile's LDS-DMA requests issued one per QK MFMA group instead of as a block at the tile top
# baseline (speedup 1.0000x reference)
; #define LAS __attribute__((address_space(3)))
; #define MFMA16(a, b, c) __builtin_amdgcn_mfma_f32_16x16x32_bf16((a), (b), (c), 0, 0, 0)
; #define AT_DMA(t, buf) do { _Pragma("unroll") for (int j_ = 0; j_ < 7; ++j_) { const int c_ = wid + 8 * j_; if (c_ < 50) { \
;             __builtin_amdgcn_global_load_lds((const unsigned*)dsrc[j_], (LAS unsigned*)(lds + (buf) * AT_BUF + 1024 * c_), 16, 0, 0); dsrc[j_] += dstr[j_]; } } } while (0)
; #define AT_SB __builtin_amdgcn_sched_barrier(0)
; #define AT_KLD(dst, ks_) do { _Pragma("unroll") for (int kvb = 0; kvb < 4; ++kvb) dst[kvb] = *(const LAS bf16x8*)(Kl + kxo[(ks_) & 3] + ((ks_) >> 2) * 256 + kvb * (16 * 512)); } while (0)
; __device__ __forceinline__ void attn_unit(const Params& P, LAS unsigned char* lds, int bh, int qb) {
;     ...
;     for (int t = 0; t < NT; ++t) {
;         const int buf = t & 1; const bool more = (t + 1 < NT);
;         if (more) AT_DMA(t + 1, buf ^ 1);
;         const LAS unsigned char* Kl = lds + buf * AT_BUF; const LAS unsigned char* Vl = Kl + AT_KB;
;         const int k0 = 64 * t;
;         if (k0 <= q0) {
;     ...
;             bf16x8 kc[4], kn[4];
;             AT_KLD(kc, 0);
;             f32x4 s[4][2];
; #pragma unroll
;             for (int kvb = 0; kvb < 4; ++kvb) { s[kvb][0] = (f32x4){-mrow[0], -mrow[0], -mrow[0], -mrow[0]}; s[kvb][1] = (f32x4){-mrow[1], -mrow[1], -mrow[1], -mrow[1]}; }
; #pragma unroll
;             for (int ks = 0; ks < 6; ++ks) {
;                 if (ks < 5) AT_KLD(kn, ks + 1);
;                 AT_SB;
; #pragma unroll
;                 for (int kvb = 0; kvb < 4; ++kvb) { s[kvb][0] = MFMA16(kc[kvb], qf[ks][0], s[kvb][0]); s[kvb][1] = MFMA16(kc[kvb], qf[ks][1], s[kvb][1]); }
;                 AT_SB;
;                 if (ks < 5) {
; #pragma unroll
;                     for (int kvb = 0; kvb < 4; ++kvb) kc[kvb] = kn[kvb]; }
;             }
.LBB0_633:
	s_add_i32 s0, s94, -1
	s_and_b32 s0, s0, 1
	s_xor_b32 s1, s0, 1
	s_mul_i32 s1, s1, 0xc800
	s_add_i32 s53, s1, s82
	s_cmp_gt_i32 s85, s81
	s_cbranch_scc0 .LBB0_642
	s_cmp_ge_u32 s94, s83
	s_cbranch_scc1 .LBB0_632
	s_add_i32 s53, s1, s82
	s_mov_b32 m0, s53
	s_nop 0
	global_load_lds_dwordx4 v[176:177], off
	s_add_i32 m0, s53, 0x2000
	v_lshl_add_u64 v[176:177], v[176:177], 0, v[178:179]
	global_load_lds_dwordx4 v[180:181], off
	s_add_i32 m0, s53, 0x4000
	v_lshl_add_u64 v[180:181], v[180:181], 0, v[182:183]
	global_load_lds_dwordx4 v[184:185], off
	s_add_i32 m0, s53, 0x6000
	v_lshl_add_u64 v[184:185], v[184:185], 0, v[186:187]
	global_load_lds_dwordx4 v[188:189], off
	s_add_i32 m0, s53, 0x8000
	v_lshl_add_u64 v[188:189], v[188:189], 0, v[190:191]
	global_load_lds_dwordx4 v[192:193], off
	s_add_i32 m0, s53, 0xa000
	v_lshl_add_u64 v[192:193], v[192:193], 0, v[194:195]
	global_load_lds_dwordx4 v[196:197], off
	v_lshl_add_u64 v[196:197], v[196:197], 0, v[198:199]
	s_andn2_b64 vcc, exec, s[74:75]
	s_cbranch_vccnz .LBB0_632
	s_add_i32 m0, s53, 0xc000
	s_nop 0
	global_load_lds_dwordx4 v[200:201], off
	v_lshl_add_u64 v[200:201], v[200:201], 0, v[202:203]
	s_branch .LBB0_632
.LBB0_642:
	s_mul_i32 s0, s0, 0xc800
	s_add_i32 s0, s0, 0
	v_add3_u32 v172, s0, v212, v211
	v_add3_u32 v206, s0, v213, v211
	ds_read_b128 v[120:123], v172
	ds_read_b128 v[124:127], v172 offset:8192
	ds_read_b128 v[128:131], v172 offset:16384
	ds_read_b128 v[132:135], v172 offset:24576
	ds_read_b128 v[140:143], v206
	ds_read_b128 v[144:147], v206 offset:8192
	ds_read_b128 v[148:151], v206 offset:16384
	ds_read_b128 v[152:155], v206 offset:24576
	s_waitcnt lgkmcnt(0)
	v_mfma_f32_16x16x32_bf16 v[160:163], v[120:123], v[0:3], v[244:247]
	v_mfma_f32_16x16x32_bf16 v[120:123], v[120:123], v[24:27], v[248:251]
	v_mfma_f32_16x16x32_bf16 v[164:167], v[124:127], v[0:3], v[244:247]
	v_mfma_f32_16x16x32_bf16 v[124:127], v[124:127], v[24:27], v[248:251]
	v_mfma_f32_16x16x32_bf16 v[220:223], v[128:131], v[0:3], v[244:247]
	v_mfma_f32_16x16x32_bf16 v[128:131], v[128:131], v[24:27], v[248:251]
	v_mfma_f32_16x16x32_bf16 v[136:139], v[132:135], v[0:3], v[244:247]
	v_mfma_f32_16x16x32_bf16 v[132:135], v[132:135], v[24:27], v[248:251]
	s_cmp_ge_u32 s94, s83
	s_cbranch_scc1 .Latt_np0
	s_mov_b32 m0, s53
	s_nop 0
	global_load_lds_dwordx4 v[176:177], off
	v_lshl_add_u64 v[176:177], v[176:177], 0, v[178:179]
.Latt_np0:
	v_add3_u32 v207, s0, v214, v211
	s_nop 1
	ds_read_b128 v[156:159], v207
	ds_read_b128 v[224:227], v207 offset:8192
	ds_read_b128 v[228:231], v207 offset:16384
	ds_read_b128 v[232:235], v207 offset:24576
	v_mfma_f32_16x16x32_bf16 v[160:163], v[140:143], v[4:7], v[160:163]
	v_mfma_f32_16x16x32_bf16 v[120:123], v[140:143], v[28:31], v[120:123]
	v_mfma_f32_16x16x32_bf16 v[140:143], v[144:147], v[4:7], v[164:167]
	v_mfma_f32_16x16x32_bf16 v[124:127], v[144:147], v[28:31], v[124:127]
	v_mfma_f32_16x16x32_bf16 v[144:147], v[148:151], v[4:7], v[220:223]
	v_mfma_f32_16x16x32_bf16 v[128:131], v[148:151], v[28:31], v[128:131]
	v_mfma_f32_16x16x32_bf16 v[136:139], v[152:155], v[4:7], v[136:139]
	v_mfma_f32_16x16x32_bf16 v[132:135], v[152:155], v[28:31], v[132:135]
	s_cmp_ge_u32 s94, s83
	s_cbranch_scc1 .Latt_np1
	s_add_i32 m0, s53, 0x2000
	s_nop 0
	global_load_lds_dwordx4 v[180:181], off
	v_lshl_add_u64 v[180:181], v[180:181], 0, v[182:183]
.Latt_np1:
	v_add3_u32 v207, s0, v216, v211
	ds_read_b128 v[148:151], v207
	ds_read_b128 v[152:155], v207 offset:8192
	ds_read_b128 v[164:167], v207 offset:16384
	ds_read_b128 v[220:223], v207 offset:24576
	s_waitcnt lgkmcnt(0)
	v_mfma_f32_16x16x32_bf16 v[160:163], v[156:159], v[8:11], v[160:163]
	v_mfma_f32_16x16x32_bf16 v[120:123], v[156:159], v[32:35], v[120:123]
	v_mfma_f32_16x16x32_bf16 v[140:143], v[224:227], v[8:11], v[140:143]
	v_mfma_f32_16x16x32_bf16 v[124:127], v[224:227], v[32:35], v[124:127]
	v_mfma_f32_16x16x32_bf16 v[144:147], v[228:231], v[8:11], v[144:147]
	v_mfma_f32_16x16x32_bf16 v[128:131], v[228:231], v[32:35], v[128:131]
	v_mfma_f32_16x16x32_bf16 v[136:139], v[232:235], v[8:11], v[136:139]
	v_mfma_f32_16x16x32_bf16 v[132:135], v[232:235], v[32:35], v[132:135]
	s_cmp_ge_u32 s94, s83
	s_cbranch_scc1 .Latt_np2
	s_add_i32 m0, s53, 0x4000
	s_nop 0
	global_load_lds_dwordx4 v[184:185], off
	v_lshl_add_u64 v[184:185], v[184:185], 0, v[186:187]
.Latt_np2:
	ds_read_b128 v[156:159], v172 offset:256
	ds_read_b128 v[224:227], v172 offset:8448
	ds_read_b128 v[228:231], v172 offset:16640
	ds_read_b128 v[232:235], v172 offset:24832
	v_mfma_f32_16x16x32_bf16 v[160:163], v[148:151], v[12:15], v[160:163]
	v_mfma_f32_16x16x32_bf16 v[120:123], v[148:151], v[36:39], v[120:123]
	v_mfma_f32_16x16x32_bf16 v[140:143], v[152:155], v[12:15], v[140:143]
	v_mfma_f32_16x16x32_bf16 v[124:127], v[152:155], v[36:39], v[124:127]
	v_mfma_f32_16x16x32_bf16 v[144:147], v[164:167], v[12:15], v[144:147]
	v_mfma_f32_16x16x32_bf16 v[128:131], v[164:167], v[36:39], v[128:131]
	v_mfma_f32_16x16x32_bf16 v[136:139], v[220:223], v[12:15], v[136:139]
	v_mfma_f32_16x16x32_bf16 v[132:135], v[220:223], v[36:39], v[132:135]
	s_cmp_ge_u32 s94, s83
	s_cbranch_scc1 .Latt_np3
	s_add_i32 m0, s53, 0x6000
	s_nop 0
	global_load_lds_dwordx4 v[188:189], off
	v_lshl_add_u64 v[188:189], v[188:189], 0, v[190:191]
; #define MFMA16(a, b, c) __builtin_amdgcn_mfma_f32_16x16x32_bf16((a), (b), (c), 0, 0, 0)
; #define AT_SB __builtin_amdgcn_sched_barrier(0)
; #define AT_KLD(dst, ks_) do { _Pragma("unroll") for (int kvb = 0; kvb < 4; ++kvb) dst[kvb] = *(const LAS bf16x8*)(Kl + kxo[(ks_) & 3] + ((ks_) >> 2) * 256 + kvb * (16 * 512)); } while (0)
; #define AT_VLD(dst, g_) do { _Pragma("unroll") for (int i_ = 0; i_ < 4; ++i_) { const LAS unsigned char* vp = Vl + (16 * (4 * ((g_) & 1) + i_) + fr) * 144 + (32 * ((g_) >> 1) + 4 * fq) * 2; \
;             const u32x2 lo = *(const LAS u32x2*)vp, hi = *(const LAS u32x2*)(vp + 32); u32x4 w; w.x = lo.x; w.y = lo.y; w.z = hi.x; w.w = hi.y; dst[i_] = __builtin_bit_cast(bf16x8, w); } } while (0)
; __device__ __forceinline__ void attn_unit(const Params& P, LAS unsigned char* lds, int bh, int qb) {
;     ...
;             for (int ks = 0; ks < 6; ++ks) {
;                 if (ks < 5) AT_KLD(kn, ks + 1);
;                 AT_SB;
; #pragma unroll
;                 for (int kvb = 0; kvb < 4; ++kvb) { s[kvb][0] = MFMA16(kc[kvb], qf[ks][0], s[kvb][0]); s[kvb][1] = MFMA16(kc[kvb], qf[ks][1], s[kvb][1]); }
;                 AT_SB;
;                 if (ks < 5) {
; #pragma unroll
;                     for (int kvb = 0; kvb < 4; ++kvb) kc[kvb] = kn[kvb]; }
;             }
;             bf16x8 vc[4], vn[4];
;             AT_VLD(vc, 0);
;             AT_SB;
;             if (k0 + 63 > q0) {
; #pragma unroll
;                 for (int kvb = 0; kvb < 4; ++kvb)
; #pragma unroll
;                     for (int qk = 0; qk < 2; ++qk)
; #pragma unroll
;                         for (int e = 0; e < 4; ++e) { const int kv = k0 + 16 * kvb + 4 * fq + e, q = q0 + 16 * qk + fr; if (kv > q) s[kvb][qk][e] = -INFINITY; }
;             }
.Latt_np3:
	ds_read_b128 v[148:151], v206 offset:256
	ds_read_b128 v[152:155], v206 offset:8448
	ds_read_b128 v[220:223], v206 offset:16640
	ds_read_b128 v[236:239], v206 offset:24832
	s_waitcnt lgkmcnt(0)
	v_mfma_f32_16x16x32_bf16 v[160:163], v[156:159], v[16:19], v[160:163]
	v_mfma_f32_16x16x32_bf16 v[120:123], v[156:159], v[40:43], v[120:123]
	v_mfma_f32_16x16x32_bf16 v[140:143], v[224:227], v[16:19], v[140:143]
	v_mfma_f32_16x16x32_bf16 v[124:127], v[224:227], v[40:43], v[124:127]
	v_mfma_f32_16x16x32_bf16 v[156:159], v[228:231], v[16:19], v[144:147]
	v_mfma_f32_16x16x32_bf16 v[128:131], v[228:231], v[40:43], v[128:131]
	v_mfma_f32_16x16x32_bf16 v[136:139], v[232:235], v[16:19], v[136:139]
	v_mfma_f32_16x16x32_bf16 v[132:135], v[232:235], v[40:43], v[132:135]
	s_cmp_ge_u32 s94, s83
	s_cbranch_scc1 .Latt_np4
	s_add_i32 m0, s53, 0x8000
	s_nop 0
	global_load_lds_dwordx4 v[192:193], off
	v_lshl_add_u64 v[192:193], v[192:193], 0, v[194:195]
.Latt_np4:
	v_mfma_f32_16x16x32_bf16 v[164:167], v[148:151], v[20:23], v[160:163]
	v_mfma_f32_16x16x32_bf16 v[148:151], v[148:151], v[44:47], v[120:123]
	v_mfma_f32_16x16x32_bf16 v[160:163], v[152:155], v[20:23], v[140:143]
	v_mfma_f32_16x16x32_bf16 v[144:147], v[152:155], v[44:47], v[124:127]
	v_mfma_f32_16x16x32_bf16 v[156:159], v[220:223], v[20:23], v[156:159]
	v_mfma_f32_16x16x32_bf16 v[140:143], v[220:223], v[44:47], v[128:131]
	v_mfma_f32_16x16x32_bf16 v[152:155], v[236:239], v[20:23], v[136:139]
	v_mfma_f32_16x16x32_bf16 v[136:139], v[236:239], v[44:47], v[132:135]
	s_cmp_ge_u32 s94, s83
	s_cbranch_scc1 .Latt_np5
	s_add_i32 m0, s53, 0xa000
	s_nop 0
	global_load_lds_dwordx4 v[196:197], off
	v_lshl_add_u64 v[196:197], v[196:197], 0, v[198:199]
.Latt_np5:
	s_cmp_ge_u32 s94, s83
	s_cbranch_scc1 .Latt_np6
	s_andn2_b64 vcc, exec, s[74:75]
	s_cbranch_vccnz .Latt_np6
	s_add_i32 m0, s53, 0xc000
	s_nop 0
	global_load_lds_dwordx4 v[200:201], off
	v_lshl_add_u64 v[200:201], v[200:201], 0, v[202:203]
.Latt_np6:
	v_add3_u32 v223, s0, v210, v218
	ds_read_b64 v[120:121], v223 offset:32768
	ds_read_b64 v[122:123], v223 offset:32800
	ds_read_b64 v[124:125], v223 offset:35072
	ds_read_b64 v[126:127], v223 offset:35104
	ds_read_b64 v[128:129], v223 offset:37376
	ds_read_b64 v[130:131], v223 offset:37408
	ds_read_b64 v[132:133], v223 offset:39680
	ds_read_b64 v[134:135], v223 offset:39712
	s_add_i32 s0, s85, 63
	s_cmp_le_i32 s0, s81
	s_cbranch_scc1 .LBB0_645
	v_add_u32_e32 v207, s85, v215
	v_cmp_gt_i32_e32 vcc, v207, v217
	v_mov_b32_e32 v206, s79
	v_cmp_lt_i32_e64 s[0:1], v207, v217
	v_cndmask_b32_e32 v206, v164, v206, vcc
	v_add_u32_e32 v224, 2, v207
	v_cndmask_b32_e64 v164, v206, v164, s[0:1]
	v_cndmask_b32_e64 v165, v209, v165, s[0:1]
	v_cmp_le_i32_e64 s[0:1], v224, v217
	v_add_u32_e32 v225, 3, v207
	v_mov_b32_e32 v206, s79
	v_cndmask_b32_e64 v166, v209, v166, s[0:1]
	v_cmp_le_i32_e64 s[0:1], v225, v217
	v_add_u32_e32 v226, 19, v207
	v_add_u32_e32 v227, 35, v207
	v_cndmask_b32_e64 v167, v209, v167, s[0:1]
	v_cmp_gt_i32_e64 s[0:1], v207, v219
	s_nop 1
	v_cndmask_b32_e64 v206, v148, v206, s[0:1]
	v_cmp_lt_i32_e64 s[0:1], v207, v219
	s_nop 1
	v_cndmask_b32_e64 v148, v206, v148, s[0:1]
	v_cndmask_b32_e64 v149, v209, v149, s[0:1]
	v_cmp_le_i32_e64 s[0:1], v224, v219
	v_add_u32_e32 v206, 16, v207
	v_add_u32_e32 v224, 17, v207
	v_cndmask_b32_e64 v150, v209, v150, s[0:1]
	v_cmp_le_i32_e64 s[0:1], v225, v219
	v_add_u32_e32 v225, 18, v207
	s_nop 0
	v_cndmask_b32_e64 v151, v209, v151, s[0:1]
	v_cmp_gt_i32_e64 s[0:1], v206, v217
	v_mov_b32_e32 v206, s79
	v_cndmask_b32_e32 v144, v144, v206, vcc
	v_cmp_le_i32_e32 vcc, v224, v219
	v_cndmask_b32_e64 v160, v160, v206, s[0:1]
	v_cmp_le_i32_e64 s[0:1], v224, v217
	v_cndmask_b32_e32 v145, v209, v145, vcc
	v_cmp_le_i32_e32 vcc, v225, v219
	v_add_u32_e32 v224, 32, v207
	v_cndmask_b32_e64 v161, v209, v161, s[0:1]
	v_cndmask_b32_e32 v146, v209, v146, vcc
	v_cmp_le_i32_e32 vcc, v226, v219
	v_cmp_le_i32_e64 s[0:1], v225, v217
	v_add_u32_e32 v225, 33, v207
	v_cndmask_b32_e32 v147, v209, v147, vcc
	v_cmp_gt_i32_e32 vcc, v224, v217
	v_cndmask_b32_e64 v162, v209, v162, s[0:1]
	v_cmp_le_i32_e64 s[0:1], v226, v217
	v_cndmask_b32_e32 v156, v156, v206, vcc
	v_cmp_le_i32_e32 vcc, v225, v217
	v_add_u32_e32 v226, 34, v207
	v_cndmask_b32_e64 v163, v209, v163, s[0:1]
	v_cndmask_b32_e32 v157, v209, v157, vcc
	v_cmp_le_i32_e32 vcc, v226, v217
	s_nop 1
	v_cndmask_b32_e32 v158, v209, v158, vcc
	v_cmp_le_i32_e32 vcc, v227, v217
	s_nop 1
	v_cndmask_b32_e32 v159, v209, v159, vcc
	v_cmp_gt_i32_e32 vcc, v224, v219
	v_add_u32_e32 v224, 48, v207
	s_nop 0
	v_cndmask_b32_e32 v140, v140, v206, vcc
	v_cmp_le_i32_e32 vcc, v225, v219
	v_add_u32_e32 v225, 49, v207
	s_nop 0
	v_cndmask_b32_e32 v141, v209, v141, vcc
	v_cmp_le_i32_e32 vcc, v226, v219
	v_add_u32_e32 v226, 50, v207
	v_add_u32_e32 v207, 51, v207
	v_cndmask_b32_e32 v142, v209, v142, vcc
	v_cmp_le_i32_e32 vcc, v227, v219
	s_nop 1
	v_cndmask_b32_e32 v143, v209, v143, vcc
	v_cmp_gt_i32_e32 vcc, v224, v217
	s_nop 1
	v_cndmask_b32_e32 v152, v152, v206, vcc
	v_cmp_le_i32_e32 vcc, v225, v217
	s_nop 1
	v_cndmask_b32_e32 v153, v209, v153, vcc
	v_cmp_le_i32_e32 vcc, v226, v217
	s_nop 1
	v_cndmask_b32_e32 v154, v209, v154, vcc
	v_cmp_le_i32_e32 vcc, v207, v217
	s_nop 1
	v_cndmask_b32_e32 v155, v209, v155, vcc
	v_cmp_gt_i32_e32 vcc, v224, v219
	s_nop 1
	v_cndmask_b32_e32 v136, v136, v206, vcc
	v_cmp_le_i32_e32 vcc, v225, v219
	s_nop 1
	v_cndmask_b32_e32 v137, v209, v137, vcc
	v_cmp_le_i32_e32 vcc, v226, v219
	s_nop 1
	v_cndmask_b32_e32 v138, v209, v138, vcc
	v_cmp_le_i32_e32 vcc, v207, v219
	s_nop 1
	v_cndmask_b32_e32 v139, v209, v139, vcc
